# scan2 (RG-LRU) loops: 16 timestep loads batched per group with counted vmcnt, chunk-prefix loads batched by 8; fused-norm epilogue drops redundant L1 invalidate
# speedup vs baseline: 1.0088x; 1.0015x over previous
; #define WG_BARRIER() do { asm volatile("s_waitcnt vmcnt(0) lgkmcnt(0)" ::: "memory"); __builtin_amdgcn_s_barrier(); asm volatile("" ::: "memory"); } while (0)
;     __device__ __forceinline__ void fused(AccT& acc, const Unit& u, int wr, int wc, int fr, int fq, LAS unsigned char* lds) const {
;     ...
;         if (wid == 0) { unsigned spins = 0;
;             while ((unsigned)__builtin_amdgcn_readfirstlane((int)__hip_atomic_load(cnt + 64 * u.pm, __ATOMIC_RELAXED, __HIP_MEMORY_SCOPE_AGENT)) < 32u) { __builtin_amdgcn_s_sleep(1); if (++spins > (1u << 22)) break; }
;             __builtin_amdgcn_fence(__ATOMIC_ACQUIRE, "agent");
;             asm volatile("s_waitcnt vmcnt(0)" ::: "memory"); }
;         WG_BARRIER();
;         if (tid < 256) { const unsigned* xp = X + ((size_t)u.pm * 256 + tid) * 8; float t = 0.f;
; #pragma unroll
;             for (int q = 0; q < 8; ++q) t += __uint_as_float(__hip_atomic_load(xp + q, __ATOMIC_RELAXED, __HIP_MEMORY_SCOPE_AGENT));
;             Ssh[tid] = rsqrtf(t * (1.0f / DM) + EPS); }
.LBB0_468:
	s_waitcnt lgkmcnt(0)
	global_load_dword v1, v0, s[14:15] sc1
	s_waitcnt vmcnt(0)
	v_readfirstlane_b32 s16, v1
	s_cmp_gt_u32 s16, 31
	s_mov_b64 s[16:17], -1
	s_cbranch_scc1 .LBB0_467
	s_sleep 1
	global_load_dword v1, v0, s[14:15] sc1
	s_waitcnt vmcnt(0)
	v_readfirstlane_b32 s16, v1
	s_cmp_lt_u32 s16, 32
	s_mov_b64 s[16:17], -1
	s_cbranch_scc0 .LBB0_467
	s_sleep 1
	global_load_dword v1, v0, s[14:15] sc1
	s_waitcnt vmcnt(0)
	v_readfirstlane_b32 s16, v1
	s_cmp_lt_u32 s16, 32
	s_mov_b64 s[16:17], -1
	s_cbranch_scc0 .LBB0_467
	s_sleep 1
	global_load_dword v1, v0, s[14:15] sc1
	s_waitcnt vmcnt(0)
	v_readfirstlane_b32 s16, v1
	s_cmp_lt_u32 s16, 32
	s_mov_b64 s[16:17], -1
	s_cbranch_scc0 .LBB0_467
	s_sleep 1
	global_load_dword v1, v0, s[14:15] sc1
	s_waitcnt vmcnt(0)
	v_readfirstlane_b32 s16, v1
	s_cmp_lt_u32 s16, 32
	s_mov_b64 s[16:17], -1
	s_cbranch_scc0 .LBB0_467
	s_add_i32 s18, s18, -5
	s_cmp_eq_u32 s18, 0
	s_cselect_b64 s[16:17], -1, 0
	s_sleep 1
	s_branch .LBB0_467
.LBB0_474:
	s_waitcnt vmcnt(0)
.LBB0_475:
	s_or_b64 exec, exec, s[10:11]
	s_waitcnt vmcnt(0) lgkmcnt(0)
	s_barrier
	s_and_saveexec_b64 s[10:11], s[0:1]
	s_cbranch_execz .LBB0_477
	s_lshl_b64 s[0:1], s[90:91], 13
	s_add_u32 s0, s28, s0
	s_addc_u32 s1, s29, s1
	s_waitcnt lgkmcnt(0)
	v_lshlrev_b64 v[0:1], 5, v[148:149]
	v_lshl_add_u64 v[0:1], s[0:1], 0, v[0:1]
	global_load_dword v2, v[0:1], off sc1
	global_load_dword v3, v[0:1], off offset:4 sc1
	global_load_dword v4, v[0:1], off offset:8 sc1
	global_load_dword v5, v[0:1], off offset:12 sc1
	global_load_dword v6, v[0:1], off offset:16 sc1
	global_load_dword v7, v[0:1], off offset:20 sc1
	global_load_dword v8, v[0:1], off offset:24 sc1
	s_nop 0
	global_load_dword v0, v[0:1], off offset:28 sc1
	v_mov_b32_e32 v1, 0x358637bd
	s_mov_b32 s0, 0x800000
	s_waitcnt vmcnt(7)
	v_add_f32_e32 v2, 0, v2
	s_waitcnt vmcnt(6)
	v_add_f32_e32 v2, v2, v3
	s_waitcnt vmcnt(5)
	v_add_f32_e32 v2, v2, v4
	s_waitcnt vmcnt(4)
	v_add_f32_e32 v2, v2, v5
	s_waitcnt vmcnt(3)
	v_add_f32_e32 v2, v2, v6
	s_waitcnt vmcnt(2)
	v_add_f32_e32 v2, v2, v7
	s_waitcnt vmcnt(1)
	v_add_f32_e32 v2, v2, v8
	s_waitcnt vmcnt(0)
	v_add_f32_e32 v0, v2, v0
	v_fmac_f32_e32 v1, 0x3a000000, v0
	v_mul_f32_e32 v0, 0x4b800000, v1
	v_cmp_gt_f32_e32 vcc, s0, v1
	s_nop 1
	v_cndmask_b32_e32 v0, v1, v0, vcc
	v_rsq_f32_e32 v0, v0
	s_nop 0
	v_mul_f32_e32 v1, 0x45800000, v0
	v_cndmask_b32_e32 v0, v0, v1, vcc
	v_lshl_add_u32 v1, v148, 2, 0
	ds_write_b32 v1, v0 offset:8192

; #define WG_BARRIER() do { asm volatile("s_waitcnt vmcnt(0) lgkmcnt(0)" ::: "memory"); __builtin_amdgcn_s_barrier(); asm volatile("" ::: "memory"); } while (0)
;     __device__ __forceinline__ void fused(AccT& acc, const Unit& u, int wr, int wc, int fr, int fq, LAS unsigned char* lds) const {
;     ...
;         if (wid == 0) { unsigned spins = 0;
;             while ((unsigned)__builtin_amdgcn_readfirstlane((int)__hip_atomic_load(cnt + 64 * u.pm, __ATOMIC_RELAXED, __HIP_MEMORY_SCOPE_AGENT)) < 32u) { __builtin_amdgcn_s_sleep(1); if (++spins > (1u << 22)) break; }
;             __builtin_amdgcn_fence(__ATOMIC_ACQUIRE, "agent");
;             asm volatile("s_waitcnt vmcnt(0)" ::: "memory"); }
;         WG_BARRIER();
;         if (tid < 256) { const unsigned* xp = X + ((size_t)u.pm * 256 + tid) * 8; float t = 0.f;
; #pragma unroll
;             for (int q = 0; q < 8; ++q) t += __uint_as_float(__hip_atomic_load(xp + q, __ATOMIC_RELAXED, __HIP_MEMORY_SCOPE_AGENT));
;             Ssh[tid] = rsqrtf(t * (1.0f / DM) + EPS); }
.LBB0_515:
	s_waitcnt lgkmcnt(0)
	global_load_dword v1, v0, s[4:5] sc1
	s_waitcnt vmcnt(0)
	v_readfirstlane_b32 s6, v1
	s_cmp_gt_u32 s6, 31
	s_mov_b64 s[6:7], -1
	s_cbranch_scc1 .LBB0_514
	s_sleep 1
	global_load_dword v1, v0, s[4:5] sc1
	s_waitcnt vmcnt(0)
	v_readfirstlane_b32 s6, v1
	s_cmp_lt_u32 s6, 32
	s_mov_b64 s[6:7], -1
	s_cbranch_scc0 .LBB0_514
	s_sleep 1
	global_load_dword v1, v0, s[4:5] sc1
	s_waitcnt vmcnt(0)
	v_readfirstlane_b32 s6, v1
	s_cmp_lt_u32 s6, 32
	s_mov_b64 s[6:7], -1
	s_cbranch_scc0 .LBB0_514
	s_sleep 1
	global_load_dword v1, v0, s[4:5] sc1
	s_waitcnt vmcnt(0)
	v_readfirstlane_b32 s6, v1
	s_cmp_lt_u32 s6, 32
	s_mov_b64 s[6:7], -1
	s_cbranch_scc0 .LBB0_514
	s_sleep 1
	global_load_dword v1, v0, s[4:5] sc1
	s_waitcnt vmcnt(0)
	v_readfirstlane_b32 s6, v1
	s_cmp_lt_u32 s6, 32
	s_mov_b64 s[6:7], -1
	s_cbranch_scc0 .LBB0_514
	s_add_i32 s18, s18, -5
	s_cmp_eq_u32 s18, 0
	s_cselect_b64 s[6:7], -1, 0
	s_sleep 1
	s_branch .LBB0_514
.LBB0_521:
	s_waitcnt vmcnt(0)
.LBB0_522:
	s_or_b64 exec, exec, s[2:3]
	s_waitcnt vmcnt(0) lgkmcnt(0)
	s_barrier
	s_and_saveexec_b64 s[2:3], s[0:1]
	s_cbranch_execz .LBB0_524
	s_lshl_b64 s[0:1], s[92:93], 13
	s_add_u32 s0, s28, s0
	s_addc_u32 s1, s29, s1
	s_waitcnt lgkmcnt(0)
	v_lshlrev_b64 v[0:1], 5, v[148:149]
	v_lshl_add_u64 v[0:1], s[0:1], 0, v[0:1]
	global_load_dword v2, v[0:1], off sc1
	global_load_dword v3, v[0:1], off offset:4 sc1
	global_load_dword v4, v[0:1], off offset:8 sc1
	global_load_dword v5, v[0:1], off offset:12 sc1
	global_load_dword v6, v[0:1], off offset:16 sc1
	global_load_dword v7, v[0:1], off offset:20 sc1
	global_load_dword v8, v[0:1], off offset:24 sc1
	s_nop 0
	global_load_dword v0, v[0:1], off offset:28 sc1
	v_mov_b32_e32 v1, 0x358637bd
	s_mov_b32 s0, 0x800000
	s_waitcnt vmcnt(7)
	v_add_f32_e32 v2, 0, v2
	s_waitcnt vmcnt(6)
	v_add_f32_e32 v2, v2, v3
	s_waitcnt vmcnt(5)
	v_add_f32_e32 v2, v2, v4
	s_waitcnt vmcnt(4)
	v_add_f32_e32 v2, v2, v5
	s_waitcnt vmcnt(3)
	v_add_f32_e32 v2, v2, v6
	s_waitcnt vmcnt(2)
	v_add_f32_e32 v2, v2, v7
	s_waitcnt vmcnt(1)
	v_add_f32_e32 v2, v2, v8
	s_waitcnt vmcnt(0)
	v_add_f32_e32 v0, v2, v0
	v_fmac_f32_e32 v1, 0x3a000000, v0
	v_mul_f32_e32 v0, 0x4b800000, v1
	v_cmp_gt_f32_e32 vcc, s0, v1
	s_nop 1
	v_cndmask_b32_e32 v0, v1, v0, vcc
	v_rsq_f32_e32 v0, v0
	s_nop 0
	v_mul_f32_e32 v1, 0x45800000, v0
	v_cndmask_b32_e32 v0, v0, v1, vcc
	v_lshl_add_u32 v1, v148, 2, 0
	ds_write_b32 v1, v0 offset:8192

; #define WG_BARRIER() do { asm volatile("s_waitcnt vmcnt(0) lgkmcnt(0)" ::: "memory"); __builtin_amdgcn_s_barrier(); asm volatile("" ::: "memory"); } while (0)
;     __device__ __forceinline__ void fused(AccT& acc, const Unit& u, int wr, int wc, int fr, int fq, LAS unsigned char* lds) const {
;     ...
;         if (wid == 0) { unsigned spins = 0;
;             while ((unsigned)__builtin_amdgcn_readfirstlane((int)__hip_atomic_load(cnt + 64 * u.pm, __ATOMIC_RELAXED, __HIP_MEMORY_SCOPE_AGENT)) < 32u) { __builtin_amdgcn_s_sleep(1); if (++spins > (1u << 22)) break; }
;             __builtin_amdgcn_fence(__ATOMIC_ACQUIRE, "agent");
;             asm volatile("s_waitcnt vmcnt(0)" ::: "memory"); }
;         WG_BARRIER();
;         if (tid < 256) { const unsigned* xp = X + ((size_t)u.pm * 256 + tid) * 8; float t = 0.f;
; #pragma unroll
;             for (int q = 0; q < 8; ++q) t += __uint_as_float(__hip_atomic_load(xp + q, __ATOMIC_RELAXED, __HIP_MEMORY_SCOPE_AGENT));
;             Ssh[tid] = rsqrtf(t * (1.0f / DM) + EPS); }
.LBB0_678:
	s_waitcnt lgkmcnt(0)
	global_load_dword v1, v0, s[34:35] sc1
	s_mov_b64 s[36:37], -1
	s_waitcnt vmcnt(0)
	v_readfirstlane_b32 s29, v1
	s_cmp_gt_u32 s29, 31
	s_cbranch_scc1 .LBB0_677
	s_sleep 1
	global_load_dword v1, v0, s[34:35] sc1
	s_waitcnt vmcnt(0)
	v_readfirstlane_b32 s29, v1
	s_cmp_lt_u32 s29, 32
	s_cbranch_scc0 .LBB0_677
	s_sleep 1
	global_load_dword v1, v0, s[34:35] sc1
	s_waitcnt vmcnt(0)
	v_readfirstlane_b32 s29, v1
	s_cmp_lt_u32 s29, 32
	s_cbranch_scc0 .LBB0_677
	s_sleep 1
	global_load_dword v1, v0, s[34:35] sc1
	s_waitcnt vmcnt(0)
	v_readfirstlane_b32 s29, v1
	s_cmp_lt_u32 s29, 32
	s_cbranch_scc0 .LBB0_677
	s_sleep 1
	global_load_dword v1, v0, s[34:35] sc1
	s_waitcnt vmcnt(0)
	v_readfirstlane_b32 s29, v1
	s_cmp_lt_u32 s29, 32
	s_cbranch_scc0 .LBB0_677
	s_add_i32 s28, s28, -5
	s_cmp_eq_u32 s28, 0
	s_cselect_b64 s[36:37], -1, 0
	s_sleep 1
	s_branch .LBB0_677
.LBB0_684:
	s_waitcnt vmcnt(0)
.LBB0_685:
	s_or_b64 exec, exec, s[20:21]
	s_waitcnt vmcnt(0) lgkmcnt(0)
	s_barrier
	s_and_saveexec_b64 s[20:21], s[0:1]
	s_cbranch_execz .LBB0_687
	s_lshl_b64 s[0:1], s[90:91], 13
	s_add_u32 s0, s33, s0
	s_addc_u32 s1, s42, s1
	s_waitcnt lgkmcnt(0)
	v_lshlrev_b64 v[0:1], 5, v[154:155]
	v_lshl_add_u64 v[0:1], s[0:1], 0, v[0:1]
	global_load_dword v2, v[0:1], off sc1
	global_load_dword v3, v[0:1], off offset:4 sc1
	global_load_dword v4, v[0:1], off offset:8 sc1
	global_load_dword v5, v[0:1], off offset:12 sc1
	global_load_dword v6, v[0:1], off offset:16 sc1
	global_load_dword v7, v[0:1], off offset:20 sc1
	global_load_dword v8, v[0:1], off offset:24 sc1
	s_nop 0
	global_load_dword v0, v[0:1], off offset:28 sc1
	v_mov_b32_e32 v1, 0x358637bd
	s_mov_b32 s0, 0x800000
	s_waitcnt vmcnt(7)
	v_add_f32_e32 v2, 0, v2
	s_waitcnt vmcnt(6)
	v_add_f32_e32 v2, v2, v3
	s_waitcnt vmcnt(5)
	v_add_f32_e32 v2, v2, v4
	s_waitcnt vmcnt(4)
	v_add_f32_e32 v2, v2, v5
	s_waitcnt vmcnt(3)
	v_add_f32_e32 v2, v2, v6
	s_waitcnt vmcnt(2)
	v_add_f32_e32 v2, v2, v7
	s_waitcnt vmcnt(1)
	v_add_f32_e32 v2, v2, v8
	s_waitcnt vmcnt(0)
	v_add_f32_e32 v0, v2, v0
	v_fmac_f32_e32 v1, 0x3a000000, v0
	v_mul_f32_e32 v0, 0x4b800000, v1
	v_cmp_gt_f32_e32 vcc, s0, v1
	s_nop 1
	v_cndmask_b32_e32 v0, v1, v0, vcc
	v_rsq_f32_e32 v0, v0
	s_nop 0
	v_mul_f32_e32 v1, 0x45800000, v0
	v_cndmask_b32_e32 v0, v0, v1, vcc
	v_lshl_add_u32 v1, v154, 2, 0
	ds_write_b32 v1, v0 offset:8192

; #define WG_BARRIER() do { asm volatile("s_waitcnt vmcnt(0) lgkmcnt(0)" ::: "memory"); __builtin_amdgcn_s_barrier(); asm volatile("" ::: "memory"); } while (0)
;     __device__ __forceinline__ void fused(AccT& acc, const Unit& u, int wr, int wc, int fr, int fq, LAS unsigned char* lds) const {
;     ...
;         if (wid == 0) { unsigned spins = 0;
;             while ((unsigned)__builtin_amdgcn_readfirstlane((int)__hip_atomic_load(cnt + 64 * u.pm, __ATOMIC_RELAXED, __HIP_MEMORY_SCOPE_AGENT)) < 32u) { __builtin_amdgcn_s_sleep(1); if (++spins > (1u << 22)) break; }
;             __builtin_amdgcn_fence(__ATOMIC_ACQUIRE, "agent");
;             asm volatile("s_waitcnt vmcnt(0)" ::: "memory"); }
;         WG_BARRIER();
;         if (tid < 256) { const unsigned* xp = X + ((size_t)u.pm * 256 + tid) * 8; float t = 0.f;
; #pragma unroll
;             for (int q = 0; q < 8; ++q) t += __uint_as_float(__hip_atomic_load(xp + q, __ATOMIC_RELAXED, __HIP_MEMORY_SCOPE_AGENT));
;             Ssh[tid] = rsqrtf(t * (1.0f / DM) + EPS); }
.LBB0_717:
	s_waitcnt lgkmcnt(0)
	global_load_dword v1, v0, s[4:5] sc1
	s_waitcnt vmcnt(0)
	v_readfirstlane_b32 s6, v1
	s_cmp_gt_u32 s6, 31
	s_mov_b64 s[6:7], -1
	s_cbranch_scc1 .LBB0_716
	s_sleep 1
	global_load_dword v1, v0, s[4:5] sc1
	s_waitcnt vmcnt(0)
	v_readfirstlane_b32 s6, v1
	s_cmp_lt_u32 s6, 32
	s_mov_b64 s[6:7], -1
	s_cbranch_scc0 .LBB0_716
	s_sleep 1
	global_load_dword v1, v0, s[4:5] sc1
	s_waitcnt vmcnt(0)
	v_readfirstlane_b32 s6, v1
	s_cmp_lt_u32 s6, 32
	s_mov_b64 s[6:7], -1
	s_cbranch_scc0 .LBB0_716
	s_sleep 1
	global_load_dword v1, v0, s[4:5] sc1
	s_waitcnt vmcnt(0)
	v_readfirstlane_b32 s6, v1
	s_cmp_lt_u32 s6, 32
	s_mov_b64 s[6:7], -1
	s_cbranch_scc0 .LBB0_716
	s_sleep 1
	global_load_dword v1, v0, s[4:5] sc1
	s_waitcnt vmcnt(0)
	v_readfirstlane_b32 s6, v1
	s_cmp_lt_u32 s6, 32
	s_mov_b64 s[6:7], -1
	s_cbranch_scc0 .LBB0_716
	s_add_i32 s28, s28, -5
	s_cmp_eq_u32 s28, 0
	s_cselect_b64 s[6:7], -1, 0
	s_sleep 1
	s_branch .LBB0_716
.LBB0_723:
	s_waitcnt vmcnt(0)
.LBB0_724:
	s_or_b64 exec, exec, s[2:3]
	s_waitcnt vmcnt(0) lgkmcnt(0)
	s_barrier
	s_and_saveexec_b64 s[2:3], s[0:1]
	s_cbranch_execz .LBB0_726
	s_lshl_b64 s[0:1], s[92:93], 13
	s_add_u32 s0, s33, s0
	s_addc_u32 s1, s42, s1
	s_waitcnt lgkmcnt(0)
	v_lshlrev_b64 v[0:1], 5, v[154:155]
	v_lshl_add_u64 v[0:1], s[0:1], 0, v[0:1]
	global_load_dword v2, v[0:1], off sc1
	global_load_dword v3, v[0:1], off offset:4 sc1
	global_load_dword v4, v[0:1], off offset:8 sc1
	global_load_dword v5, v[0:1], off offset:12 sc1
	global_load_dword v6, v[0:1], off offset:16 sc1
	global_load_dword v7, v[0:1], off offset:20 sc1
	global_load_dword v8, v[0:1], off offset:24 sc1
	s_nop 0
	global_load_dword v0, v[0:1], off offset:28 sc1
	v_mov_b32_e32 v1, 0x358637bd
	s_mov_b32 s0, 0x800000
	s_waitcnt vmcnt(7)
	v_add_f32_e32 v2, 0, v2
	s_waitcnt vmcnt(6)
	v_add_f32_e32 v2, v2, v3
	s_waitcnt vmcnt(5)
	v_add_f32_e32 v2, v2, v4
	s_waitcnt vmcnt(4)
	v_add_f32_e32 v2, v2, v5
	s_waitcnt vmcnt(3)
	v_add_f32_e32 v2, v2, v6
	s_waitcnt vmcnt(2)
	v_add_f32_e32 v2, v2, v7
	s_waitcnt vmcnt(1)
	v_add_f32_e32 v2, v2, v8
	s_waitcnt vmcnt(0)
	v_add_f32_e32 v0, v2, v0
	v_fmac_f32_e32 v1, 0x3a000000, v0
	v_mul_f32_e32 v0, 0x4b800000, v1
	v_cmp_gt_f32_e32 vcc, s0, v1
	s_nop 1
	v_cndmask_b32_e32 v0, v1, v0, vcc
	v_rsq_f32_e32 v0, v0
	s_nop 0
	v_mul_f32_e32 v1, 0x45800000, v0
	v_cndmask_b32_e32 v0, v0, v1, vcc
	v_lshl_add_u32 v1, v154, 2, 0
	ds_write_b32 v1, v0 offset:8192

; __device__ __forceinline__ unsigned cvt_pk_bf16(float lo, float hi) { const bf16x2_t r = __builtin_convertvector((f32x2){lo, hi}, bf16x2_t); return __builtin_bit_cast(unsigned, r); }
; __device__ __forceinline__ float bf_lo(unsigned w) { return __uint_as_float(w << 16); }
; __device__ __forceinline__ float bf_hi(unsigned w) { return __uint_as_float(w & 0xffff0000u); }
; __device__ __forceinline__ int opaque_tid() { int t = threadIdx.x; asm volatile("" : "+v"(t)); return t; }
; __device__ __forceinline__ void scan2_phase(const unsigned* AU, const float* PA, const float* PH, const bf16_t* GB, bf16_t* AB) {
;     const int nth = gridDim.x * 512;
;     for (int idx = blockIdx.x * 512 + opaque_tid(); idx < NBATCH * SCH * 1024; idx += nth) {
;         const int ch = (idx & 1023) * 2, cc = (idx >> 10) & (SCH - 1), bb = idx >> 15;
;         float h0 = 0.f, h1 = 0.f;
;         for (int q = 0; q < cc; ++q) { const size_t o = (size_t)(bb * SCH + q) * DM + ch; const f32x2 pa = *(const f32x2*)(PA + o), ph = *(const f32x2*)(PH + o);
;             h0 = pa[0] * h0 + ph[0]; h1 = pa[1] * h1 + ph[1]; }
;         const size_t base = (size_t)(bb * SEQ + cc * SCL) * DM + ch;
; #pragma unroll 16
;         for (int t = 0; t < SCL; ++t) { const u32x2 w = *(const u32x2*)(AU + base + (size_t)t * DM);
;             const unsigned g = *(const unsigned*)(GB + base + (size_t)t * DM);
;             h0 = (1.0f - bf_lo(w.x)) * h0 + bf_hi(w.x); h1 = (1.0f - bf_lo(w.y)) * h1 + bf_hi(w.y);
;             *(unsigned*)(AB + base + (size_t)t * DM) = cvt_pk_bf16(h0 * bf_lo(g), h1 * bf_hi(g)); }
;     }
.LBB0_1016:
	v_bfe_u32 v4, v12, 10, 5
	v_lshlrev_b32_e32 v1, 1, v12
	v_and_b32_e32 v6, 0x7fe, v1
	v_ashrrev_i32_e32 v5, 15, v12
	v_lshlrev_b32_e32 v2, 18, v5
	v_lshlrev_b32_e32 v7, 2, v13
	s_movk_i32 s28, 0x1ff8
	v_and_or_b32 v2, v7, s28, v2
	v_mov_b32_e32 v8, 0
	v_mov_b32_e32 v9, 0
	v_readfirstlane_b32 s45, v4
	s_mov_b64 s[98:99], s[0:1]
	s_add_u32 s100, s0, 0x100000
	s_addc_u32 s101, s1, 0
.Lsc2_pre_top:
	s_cmp_eq_u32 s45, 0
	s_cbranch_scc1 .Lsc2_pre_done
	global_load_dwordx2 v[32:33], v2, s[98:99]
	global_load_dwordx2 v[34:35], v2, s[100:101]
	s_add_u32 s98, s98, 0x2000
	s_addc_u32 s99, s99, 0
	s_add_u32 s100, s100, 0x2000
	s_addc_u32 s101, s101, 0
	global_load_dwordx2 v[36:37], v2, s[98:99]
	global_load_dwordx2 v[38:39], v2, s[100:101]
	s_add_u32 s98, s98, 0x2000
	s_addc_u32 s99, s99, 0
	s_add_u32 s100, s100, 0x2000
	s_addc_u32 s101, s101, 0
	global_load_dwordx2 v[40:41], v2, s[98:99]
	global_load_dwordx2 v[42:43], v2, s[100:101]
	s_add_u32 s98, s98, 0x2000
	s_addc_u32 s99, s99, 0
	s_add_u32 s100, s100, 0x2000
	s_addc_u32 s101, s101, 0
	global_load_dwordx2 v[44:45], v2, s[98:99]
	global_load_dwordx2 v[46:47], v2, s[100:101]
	s_add_u32 s98, s98, 0x2000
	s_addc_u32 s99, s99, 0
	s_add_u32 s100, s100, 0x2000
	s_addc_u32 s101, s101, 0
	global_load_dwordx2 v[48:49], v2, s[98:99]
	global_load_dwordx2 v[50:51], v2, s[100:101]
	s_add_u32 s98, s98, 0x2000
	s_addc_u32 s99, s99, 0
	s_add_u32 s100, s100, 0x2000
	s_addc_u32 s101, s101, 0
	global_load_dwordx2 v[52:53], v2, s[98:99]
	global_load_dwordx2 v[54:55], v2, s[100:101]
	s_add_u32 s98, s98, 0x2000
	s_addc_u32 s99, s99, 0
	s_add_u32 s100, s100, 0x2000
	s_addc_u32 s101, s101, 0
	global_load_dwordx2 v[56:57], v2, s[98:99]
	global_load_dwordx2 v[58:59], v2, s[100:101]
	s_add_u32 s98, s98, 0x2000
	s_addc_u32 s99, s99, 0
	s_add_u32 s100, s100, 0x2000
	s_addc_u32 s101, s101, 0
	global_load_dwordx2 v[60:61], v2, s[98:99]
	global_load_dwordx2 v[62:63], v2, s[100:101]
	s_add_u32 s98, s98, 0x2000
	s_addc_u32 s99, s99, 0
	s_add_u32 s100, s100, 0x2000
	s_addc_u32 s101, s101, 0
	s_waitcnt vmcnt(14)
	v_pk_fma_f32 v[8:9], v[8:9], v[32:33], v[34:35]
	s_add_i32 s45, s45, -1
	s_cmp_eq_u32 s45, 0
	s_cbranch_scc1 .Lsc2_pre_done
	s_waitcnt vmcnt(12)
	v_pk_fma_f32 v[8:9], v[8:9], v[36:37], v[38:39]
	s_add_i32 s45, s45, -1
	s_cmp_eq_u32 s45, 0
	s_cbranch_scc1 .Lsc2_pre_done
	s_waitcnt vmcnt(10)
	v_pk_fma_f32 v[8:9], v[8:9], v[40:41], v[42:43]
	s_add_i32 s45, s45, -1
	s_cmp_eq_u32 s45, 0
	s_cbranch_scc1 .Lsc2_pre_done
	s_waitcnt vmcnt(8)
	v_pk_fma_f32 v[8:9], v[8:9], v[44:45], v[46:47]
	s_add_i32 s45, s45, -1
	s_cmp_eq_u32 s45, 0
	s_cbranch_scc1 .Lsc2_pre_done
	s_waitcnt vmcnt(6)
	v_pk_fma_f32 v[8:9], v[8:9], v[48:49], v[50:51]
	s_add_i32 s45, s45, -1
	s_cmp_eq_u32 s45, 0
	s_cbranch_scc1 .Lsc2_pre_done
	s_waitcnt vmcnt(4)
	v_pk_fma_f32 v[8:9], v[8:9], v[52:53], v[54:55]
	s_add_i32 s45, s45, -1
	s_cmp_eq_u32 s45, 0
	s_cbranch_scc1 .Lsc2_pre_done
	s_waitcnt vmcnt(2)
	v_pk_fma_f32 v[8:9], v[8:9], v[56:57], v[58:59]
	s_add_i32 s45, s45, -1
	s_cmp_eq_u32 s45, 0
	s_cbranch_scc1 .Lsc2_pre_done
	s_waitcnt vmcnt(0)
	v_pk_fma_f32 v[8:9], v[8:9], v[60:61], v[62:63]
	s_add_i32 s45, s45, -1
	s_branch .Lsc2_pre_top
.Lsc2_pre_done:
	v_lshlrev_b32_e32 v1, 7, v4
	v_lshl_or_b32 v4, v5, 12, v1
	v_lshlrev_b32_e32 v2, 12, v4
	v_lshlrev_b32_e32 v4, 13, v4
	v_lshl_or_b32 v2, v6, 1, v2
	v_lshl_or_b32 v4, v6, 2, v4
	s_add_u32 s98, s78, 0x24500000
	s_addc_u32 s99, s79, 0
	s_add_u32 s100, s78, 0x1c500000
	s_addc_u32 s101, s79, 0
	s_add_u32 s28, s78, 0x20500000
	s_addc_u32 s29, s79, 0
	s_movk_i32 s44, 8
.Lsc2_top:
	global_load_dwordx2 v[32:33], v4, s[98:99]
	global_load_dword v64, v2, s[100:101]
	s_add_u32 s98, s98, 0x2000
	s_addc_u32 s99, s99, 0
	s_add_u32 s100, s100, 0x1000
	s_addc_u32 s101, s101, 0
	global_load_dwordx2 v[34:35], v4, s[98:99]
	global_load_dword v65, v2, s[100:101]
	s_add_u32 s98, s98, 0x2000
	s_addc_u32 s99, s99, 0
	s_add_u32 s100, s100, 0x1000
	s_addc_u32 s101, s101, 0
	global_load_dwordx2 v[36:37], v4, s[98:99]
	global_load_dword v66, v2, s[100:101]
	s_add_u32 s98, s98, 0x2000
	s_addc_u32 s99, s99, 0
	s_add_u32 s100, s100, 0x1000
	s_addc_u32 s101, s101, 0
	global_load_dwordx2 v[38:39], v4, s[98:99]
	global_load_dword v67, v2, s[100:101]
	s_add_u32 s98, s98, 0x2000
	s_addc_u32 s99, s99, 0
	s_add_u32 s100, s100, 0x1000
	s_addc_u32 s101, s101, 0
	global_load_dwordx2 v[40:41], v4, s[98:99]
	global_load_dword v68, v2, s[100:101]
	s_add_u32 s98, s98, 0x2000
	s_addc_u32 s99, s99, 0
	s_add_u32 s100, s100, 0x1000
	s_addc_u32 s101, s101, 0
	global_load_dwordx2 v[42:43], v4, s[98:99]
	global_load_dword v69, v2, s[100:101]
	s_add_u32 s98, s98, 0x2000
	s_addc_u32 s99, s99, 0
	s_add_u32 s100, s100, 0x1000
	s_addc_u32 s101, s101, 0
	global_load_dwordx2 v[44:45], v4, s[98:99]
	global_load_dword v70, v2, s[100:101]
	s_add_u32 s98, s98, 0x2000
	s_addc_u32 s99, s99, 0
	s_add_u32 s100, s100, 0x1000
	s_addc_u32 s101, s101, 0
	global_load_dwordx2 v[46:47], v4, s[98:99]
	global_load_dword v71, v2, s[100:101]
	s_add_u32 s98, s98, 0x2000
	s_addc_u32 s99, s99, 0
	s_add_u32 s100, s100, 0x1000
	s_addc_u32 s101, s101, 0
	global_load_dwordx2 v[48:49], v4, s[98:99]
	global_load_dword v72, v2, s[100:101]
	s_add_u32 s98, s98, 0x2000
	s_addc_u32 s99, s99, 0
	s_add_u32 s100, s100, 0x1000
	s_addc_u32 s101, s101, 0
	global_load_dwordx2 v[50:51], v4, s[98:99]
	global_load_dword v73, v2, s[100:101]
	s_add_u32 s98, s98, 0x2000
	s_addc_u32 s99, s99, 0
	s_add_u32 s100, s100, 0x1000
	s_addc_u32 s101, s101, 0
	global_load_dwordx2 v[52:53], v4, s[98:99]
	global_load_dword v74, v2, s[100:101]
	s_add_u32 s98, s98, 0x2000
	s_addc_u32 s99, s99, 0
	s_add_u32 s100, s100, 0x1000
	s_addc_u32 s101, s101, 0
	global_load_dwordx2 v[54:55], v4, s[98:99]
	global_load_dword v75, v2, s[100:101]
	s_add_u32 s98, s98, 0x2000
	s_addc_u32 s99, s99, 0
	s_add_u32 s100, s100, 0x1000
	s_addc_u32 s101, s101, 0
	global_load_dwordx2 v[56:57], v4, s[98:99]
	global_load_dword v76, v2, s[100:101]
	s_add_u32 s98, s98, 0x2000
	s_addc_u32 s99, s99, 0
	s_add_u32 s100, s100, 0x1000
	s_addc_u32 s101, s101, 0
	global_load_dwordx2 v[58:59], v4, s[98:99]
	global_load_dword v77, v2, s[100:101]
	s_add_u32 s98, s98, 0x2000
	s_addc_u32 s99, s99, 0
	s_add_u32 s100, s100, 0x1000
	s_addc_u32 s101, s101, 0
	global_load_dwordx2 v[60:61], v4, s[98:99]
	global_load_dword v78, v2, s[100:101]
	s_add_u32 s98, s98, 0x2000
	s_addc_u32 s99, s99, 0
	s_add_u32 s100, s100, 0x1000
	s_addc_u32 s101, s101, 0
	global_load_dwordx2 v[62:63], v4, s[98:99]
	global_load_dword v79, v2, s[100:101]
	s_add_u32 s98, s98, 0x2000
	s_addc_u32 s99, s99, 0
	s_add_u32 s100, s100, 0x1000
	s_addc_u32 s101, s101, 0
	s_waitcnt vmcnt(30)
; __device__ __forceinline__ unsigned cvt_pk_bf16(float lo, float hi) { const bf16x2_t r = __builtin_convertvector((f32x2){lo, hi}, bf16x2_t); return __builtin_bit_cast(unsigned, r); }
; __device__ __forceinline__ float bf_lo(unsigned w) { return __uint_as_float(w << 16); }
; __device__ __forceinline__ float bf_hi(unsigned w) { return __uint_as_float(w & 0xffff0000u); }
; __device__ __forceinline__ void scan2_phase(const unsigned* AU, const float* PA, const float* PH, const bf16_t* GB, bf16_t* AB) {
;     ...
;         for (int t = 0; t < SCL; ++t) { const u32x2 w = *(const u32x2*)(AU + base + (size_t)t * DM);
;             const unsigned g = *(const unsigned*)(GB + base + (size_t)t * DM);
;             h0 = (1.0f - bf_lo(w.x)) * h0 + bf_hi(w.x); h1 = (1.0f - bf_lo(w.y)) * h1 + bf_hi(w.y);
;             *(unsigned*)(AB + base + (size_t)t * DM) = cvt_pk_bf16(h0 * bf_lo(g), h1 * bf_hi(g)); }
	v_lshlrev_b32_e32 v17, 16, v33
	v_lshlrev_b32_e32 v16, 16, v32
	v_pk_add_f32 v[16:17], v[16:17], 1.0 op_sel_hi:[1,0] neg_lo:[1,0] neg_hi:[1,0]
	v_and_b32_e32 v19, 0xffff0000, v33
	v_and_b32_e32 v18, 0xffff0000, v32
	v_pk_fma_f32 v[8:9], v[8:9], v[16:17], v[18:19]
	v_lshlrev_b32_e32 v20, 16, v64
	v_and_b32_e32 v21, 0xffff0000, v64
	v_pk_mul_f32 v[20:21], v[8:9], v[20:21]
	s_nop 0
	v_cvt_pk_bf16_f32 v64, v20, v21
	global_store_dword v2, v64, s[28:29]
	s_add_u32 s28, s28, 0x1000
	s_addc_u32 s29, s29, 0
	s_waitcnt vmcnt(29)
	v_lshlrev_b32_e32 v17, 16, v35
	v_lshlrev_b32_e32 v16, 16, v34
	v_pk_add_f32 v[16:17], v[16:17], 1.0 op_sel_hi:[1,0] neg_lo:[1,0] neg_hi:[1,0]
	v_and_b32_e32 v19, 0xffff0000, v35
	v_and_b32_e32 v18, 0xffff0000, v34
	v_pk_fma_f32 v[8:9], v[8:9], v[16:17], v[18:19]
	v_lshlrev_b32_e32 v20, 16, v65
	v_and_b32_e32 v21, 0xffff0000, v65
	v_pk_mul_f32 v[20:21], v[8:9], v[20:21]
	s_nop 0
	v_cvt_pk_bf16_f32 v65, v20, v21
	global_store_dword v2, v65, s[28:29]
	s_add_u32 s28, s28, 0x1000
	s_addc_u32 s29, s29, 0
	s_waitcnt vmcnt(28)
	v_lshlrev_b32_e32 v17, 16, v37
	v_lshlrev_b32_e32 v16, 16, v36
	v_pk_add_f32 v[16:17], v[16:17], 1.0 op_sel_hi:[1,0] neg_lo:[1,0] neg_hi:[1,0]
	v_and_b32_e32 v19, 0xffff0000, v37
	v_and_b32_e32 v18, 0xffff0000, v36
	v_pk_fma_f32 v[8:9], v[8:9], v[16:17], v[18:19]
	v_lshlrev_b32_e32 v20, 16, v66
	v_and_b32_e32 v21, 0xffff0000, v66
	v_pk_mul_f32 v[20:21], v[8:9], v[20:21]
	s_nop 0
	v_cvt_pk_bf16_f32 v66, v20, v21
	global_store_dword v2, v66, s[28:29]
	s_add_u32 s28, s28, 0x1000
	s_addc_u32 s29, s29, 0
	s_waitcnt vmcnt(27)
	v_lshlrev_b32_e32 v17, 16, v39
	v_lshlrev_b32_e32 v16, 16, v38
	v_pk_add_f32 v[16:17], v[16:17], 1.0 op_sel_hi:[1,0] neg_lo:[1,0] neg_hi:[1,0]
	v_and_b32_e32 v19, 0xffff0000, v39
	v_and_b32_e32 v18, 0xffff0000, v38
	v_pk_fma_f32 v[8:9], v[8:9], v[16:17], v[18:19]
	v_lshlrev_b32_e32 v20, 16, v67
	v_and_b32_e32 v21, 0xffff0000, v67
	v_pk_mul_f32 v[20:21], v[8:9], v[20:21]
	s_nop 0
	v_cvt_pk_bf16_f32 v67, v20, v21
	global_store_dword v2, v67, s[28:29]
	s_add_u32 s28, s28, 0x1000
	s_addc_u32 s29, s29, 0
	s_waitcnt vmcnt(26)
	v_lshlrev_b32_e32 v17, 16, v41
	v_lshlrev_b32_e32 v16, 16, v40
	v_pk_add_f32 v[16:17], v[16:17], 1.0 op_sel_hi:[1,0] neg_lo:[1,0] neg_hi:[1,0]
	v_and_b32_e32 v19, 0xffff0000, v41
	v_and_b32_e32 v18, 0xffff0000, v40
	v_pk_fma_f32 v[8:9], v[8:9], v[16:17], v[18:19]
	v_lshlrev_b32_e32 v20, 16, v68
	v_and_b32_e32 v21, 0xffff0000, v68
	v_pk_mul_f32 v[20:21], v[8:9], v[20:21]
	s_nop 0
	v_cvt_pk_bf16_f32 v68, v20, v21
	global_store_dword v2, v68, s[28:29]
	s_add_u32 s28, s28, 0x1000
	s_addc_u32 s29, s29, 0
	s_waitcnt vmcnt(25)
	v_lshlrev_b32_e32 v17, 16, v43
	v_lshlrev_b32_e32 v16, 16, v42
	v_pk_add_f32 v[16:17], v[16:17], 1.0 op_sel_hi:[1,0] neg_lo:[1,0] neg_hi:[1,0]
	v_and_b32_e32 v19, 0xffff0000, v43
	v_and_b32_e32 v18, 0xffff0000, v42
	v_pk_fma_f32 v[8:9], v[8:9], v[16:17], v[18:19]
	v_lshlrev_b32_e32 v20, 16, v69
	v_and_b32_e32 v21, 0xffff0000, v69
	v_pk_mul_f32 v[20:21], v[8:9], v[20:21]
	s_nop 0
	v_cvt_pk_bf16_f32 v69, v20, v21
	global_store_dword v2, v69, s[28:29]
	s_add_u32 s28, s28, 0x1000
	s_addc_u32 s29, s29, 0
	s_waitcnt vmcnt(24)
	v_lshlrev_b32_e32 v17, 16, v45
	v_lshlrev_b32_e32 v16, 16, v44
	v_pk_add_f32 v[16:17], v[16:17], 1.0 op_sel_hi:[1,0] neg_lo:[1,0] neg_hi:[1,0]
	v_and_b32_e32 v19, 0xffff0000, v45
	v_and_b32_e32 v18, 0xffff0000, v44
	v_pk_fma_f32 v[8:9], v[8:9], v[16:17], v[18:19]
	v_lshlrev_b32_e32 v20, 16, v70
	v_and_b32_e32 v21, 0xffff0000, v70
	v_pk_mul_f32 v[20:21], v[8:9], v[20:21]
	s_nop 0
	v_cvt_pk_bf16_f32 v70, v20, v21
	global_store_dword v2, v70, s[28:29]
	s_add_u32 s28, s28, 0x1000
	s_addc_u32 s29, s29, 0
	s_waitcnt vmcnt(23)
	v_lshlrev_b32_e32 v17, 16, v47
	v_lshlrev_b32_e32 v16, 16, v46
	v_pk_add_f32 v[16:17], v[16:17], 1.0 op_sel_hi:[1,0] neg_lo:[1,0] neg_hi:[1,0]
	v_and_b32_e32 v19, 0xffff0000, v47
	v_and_b32_e32 v18, 0xffff0000, v46
	v_pk_fma_f32 v[8:9], v[8:9], v[16:17], v[18:19]
	v_lshlrev_b32_e32 v20, 16, v71
	v_and_b32_e32 v21, 0xffff0000, v71
	v_pk_mul_f32 v[20:21], v[8:9], v[20:21]
	s_nop 0
	v_cvt_pk_bf16_f32 v71, v20, v21
	global_store_dword v2, v71, s[28:29]
	s_add_u32 s28, s28, 0x1000
	s_addc_u32 s29, s29, 0
	s_waitcnt vmcnt(22)
; __device__ __forceinline__ unsigned cvt_pk_bf16(float lo, float hi) { const bf16x2_t r = __builtin_convertvector((f32x2){lo, hi}, bf16x2_t); return __builtin_bit_cast(unsigned, r); }
; __device__ __forceinline__ float bf_lo(unsigned w) { return __uint_as_float(w << 16); }
; __device__ __forceinline__ float bf_hi(unsigned w) { return __uint_as_float(w & 0xffff0000u); }
; __device__ __forceinline__ void scan2_phase(const unsigned* AU, const float* PA, const float* PH, const bf16_t* GB, bf16_t* AB) {
;     ...
; #pragma unroll 16
;         for (int t = 0; t < SCL; ++t) { const u32x2 w = *(const u32x2*)(AU + base + (size_t)t * DM);
;             const unsigned g = *(const unsigned*)(GB + base + (size_t)t * DM);
;             h0 = (1.0f - bf_lo(w.x)) * h0 + bf_hi(w.x); h1 = (1.0f - bf_lo(w.y)) * h1 + bf_hi(w.y);
;             *(unsigned*)(AB + base + (size_t)t * DM) = cvt_pk_bf16(h0 * bf_lo(g), h1 * bf_hi(g)); }
;     }
	v_lshlrev_b32_e32 v17, 16, v49
	v_lshlrev_b32_e32 v16, 16, v48
	v_pk_add_f32 v[16:17], v[16:17], 1.0 op_sel_hi:[1,0] neg_lo:[1,0] neg_hi:[1,0]
	v_and_b32_e32 v19, 0xffff0000, v49
	v_and_b32_e32 v18, 0xffff0000, v48
	v_pk_fma_f32 v[8:9], v[8:9], v[16:17], v[18:19]
	v_lshlrev_b32_e32 v20, 16, v72
	v_and_b32_e32 v21, 0xffff0000, v72
	v_pk_mul_f32 v[20:21], v[8:9], v[20:21]
	s_nop 0
	v_cvt_pk_bf16_f32 v72, v20, v21
	global_store_dword v2, v72, s[28:29]
	s_add_u32 s28, s28, 0x1000
	s_addc_u32 s29, s29, 0
	s_waitcnt vmcnt(21)
	v_lshlrev_b32_e32 v17, 16, v51
	v_lshlrev_b32_e32 v16, 16, v50
	v_pk_add_f32 v[16:17], v[16:17], 1.0 op_sel_hi:[1,0] neg_lo:[1,0] neg_hi:[1,0]
	v_and_b32_e32 v19, 0xffff0000, v51
	v_and_b32_e32 v18, 0xffff0000, v50
	v_pk_fma_f32 v[8:9], v[8:9], v[16:17], v[18:19]
	v_lshlrev_b32_e32 v20, 16, v73
	v_and_b32_e32 v21, 0xffff0000, v73
	v_pk_mul_f32 v[20:21], v[8:9], v[20:21]
	s_nop 0
	v_cvt_pk_bf16_f32 v73, v20, v21
	global_store_dword v2, v73, s[28:29]
	s_add_u32 s28, s28, 0x1000
	s_addc_u32 s29, s29, 0
	s_waitcnt vmcnt(20)
	v_lshlrev_b32_e32 v17, 16, v53
	v_lshlrev_b32_e32 v16, 16, v52
	v_pk_add_f32 v[16:17], v[16:17], 1.0 op_sel_hi:[1,0] neg_lo:[1,0] neg_hi:[1,0]
	v_and_b32_e32 v19, 0xffff0000, v53
	v_and_b32_e32 v18, 0xffff0000, v52
	v_pk_fma_f32 v[8:9], v[8:9], v[16:17], v[18:19]
	v_lshlrev_b32_e32 v20, 16, v74
	v_and_b32_e32 v21, 0xffff0000, v74
	v_pk_mul_f32 v[20:21], v[8:9], v[20:21]
	s_nop 0
	v_cvt_pk_bf16_f32 v74, v20, v21
	global_store_dword v2, v74, s[28:29]
	s_add_u32 s28, s28, 0x1000
	s_addc_u32 s29, s29, 0
	s_waitcnt vmcnt(19)
	v_lshlrev_b32_e32 v17, 16, v55
	v_lshlrev_b32_e32 v16, 16, v54
	v_pk_add_f32 v[16:17], v[16:17], 1.0 op_sel_hi:[1,0] neg_lo:[1,0] neg_hi:[1,0]
	v_and_b32_e32 v19, 0xffff0000, v55
	v_and_b32_e32 v18, 0xffff0000, v54
	v_pk_fma_f32 v[8:9], v[8:9], v[16:17], v[18:19]
	v_lshlrev_b32_e32 v20, 16, v75
	v_and_b32_e32 v21, 0xffff0000, v75
	v_pk_mul_f32 v[20:21], v[8:9], v[20:21]
	s_nop 0
	v_cvt_pk_bf16_f32 v75, v20, v21
	global_store_dword v2, v75, s[28:29]
	s_add_u32 s28, s28, 0x1000
	s_addc_u32 s29, s29, 0
	s_waitcnt vmcnt(18)
	v_lshlrev_b32_e32 v17, 16, v57
	v_lshlrev_b32_e32 v16, 16, v56
	v_pk_add_f32 v[16:17], v[16:17], 1.0 op_sel_hi:[1,0] neg_lo:[1,0] neg_hi:[1,0]
	v_and_b32_e32 v19, 0xffff0000, v57
	v_and_b32_e32 v18, 0xffff0000, v56
	v_pk_fma_f32 v[8:9], v[8:9], v[16:17], v[18:19]
	v_lshlrev_b32_e32 v20, 16, v76
	v_and_b32_e32 v21, 0xffff0000, v76
	v_pk_mul_f32 v[20:21], v[8:9], v[20:21]
	s_nop 0
	v_cvt_pk_bf16_f32 v76, v20, v21
	global_store_dword v2, v76, s[28:29]
	s_add_u32 s28, s28, 0x1000
	s_addc_u32 s29, s29, 0
	s_waitcnt vmcnt(17)
	v_lshlrev_b32_e32 v17, 16, v59
	v_lshlrev_b32_e32 v16, 16, v58
	v_pk_add_f32 v[16:17], v[16:17], 1.0 op_sel_hi:[1,0] neg_lo:[1,0] neg_hi:[1,0]
	v_and_b32_e32 v19, 0xffff0000, v59
	v_and_b32_e32 v18, 0xffff0000, v58
	v_pk_fma_f32 v[8:9], v[8:9], v[16:17], v[18:19]
	v_lshlrev_b32_e32 v20, 16, v77
	v_and_b32_e32 v21, 0xffff0000, v77
	v_pk_mul_f32 v[20:21], v[8:9], v[20:21]
	s_nop 0
	v_cvt_pk_bf16_f32 v77, v20, v21
	global_store_dword v2, v77, s[28:29]
	s_add_u32 s28, s28, 0x1000
	s_addc_u32 s29, s29, 0
	s_waitcnt vmcnt(16)
	v_lshlrev_b32_e32 v17, 16, v61
	v_lshlrev_b32_e32 v16, 16, v60
	v_pk_add_f32 v[16:17], v[16:17], 1.0 op_sel_hi:[1,0] neg_lo:[1,0] neg_hi:[1,0]
	v_and_b32_e32 v19, 0xffff0000, v61
	v_and_b32_e32 v18, 0xffff0000, v60
	v_pk_fma_f32 v[8:9], v[8:9], v[16:17], v[18:19]
	v_lshlrev_b32_e32 v20, 16, v78
	v_and_b32_e32 v21, 0xffff0000, v78
	v_pk_mul_f32 v[20:21], v[8:9], v[20:21]
	s_nop 0
	v_cvt_pk_bf16_f32 v78, v20, v21
	global_store_dword v2, v78, s[28:29]
	s_add_u32 s28, s28, 0x1000
	s_addc_u32 s29, s29, 0
	s_waitcnt vmcnt(15)
	v_lshlrev_b32_e32 v17, 16, v63
	v_lshlrev_b32_e32 v16, 16, v62
	v_pk_add_f32 v[16:17], v[16:17], 1.0 op_sel_hi:[1,0] neg_lo:[1,0] neg_hi:[1,0]
	v_and_b32_e32 v19, 0xffff0000, v63
	v_and_b32_e32 v18, 0xffff0000, v62
	v_pk_fma_f32 v[8:9], v[8:9], v[16:17], v[18:19]
	v_lshlrev_b32_e32 v20, 16, v79
	v_and_b32_e32 v21, 0xffff0000, v79
	v_pk_mul_f32 v[20:21], v[8:9], v[20:21]
	s_nop 0
	v_cvt_pk_bf16_f32 v79, v20, v21
	global_store_dword v2, v79, s[28:29]
	s_add_u32 s28, s28, 0x1000
	s_addc_u32 s29, s29, 0
	s_add_i32 s44, s44, -1
	s_cmp_eq_u32 s44, 0
	s_cbranch_scc0 .Lsc2_top
	v_add_u32_e32 v12, s33, v12
	v_cmp_lt_i32_e32 vcc, s69, v12
	s_or_b64 s[4:5], vcc, s[4:5]
	v_add_u32_e32 v13, s48, v13
	s_andn2_b64 exec, exec, s[4:5]
	s_cbranch_execnz .LBB0_1016

; #define WG_BARRIER() do { asm volatile("s_waitcnt vmcnt(0) lgkmcnt(0)" ::: "memory"); __builtin_amdgcn_s_barrier(); asm volatile("" ::: "memory"); } while (0)
;     __device__ __forceinline__ void fused(AccT& acc, const Unit& u, int wr, int wc, int fr, int fq, LAS unsigned char* lds) const {
;     ...
;         if (wid == 0) { unsigned spins = 0;
;             while ((unsigned)__builtin_amdgcn_readfirstlane((int)__hip_atomic_load(cnt + 64 * u.pm, __ATOMIC_RELAXED, __HIP_MEMORY_SCOPE_AGENT)) < 32u) { __builtin_amdgcn_s_sleep(1); if (++spins > (1u << 22)) break; }
;             __builtin_amdgcn_fence(__ATOMIC_ACQUIRE, "agent");
;             asm volatile("s_waitcnt vmcnt(0)" ::: "memory"); }
;         WG_BARRIER();
;         if (tid < 256) { const unsigned* xp = X + ((size_t)u.pm * 256 + tid) * 8; float t = 0.f;
; #pragma unroll
;             for (int q = 0; q < 8; ++q) t += __uint_as_float(__hip_atomic_load(xp + q, __ATOMIC_RELAXED, __HIP_MEMORY_SCOPE_AGENT));
;             Ssh[tid] = rsqrtf(t * (1.0f / DM) + EPS); }
.LBB0_1108:
	s_waitcnt lgkmcnt(0)
	global_load_dword v1, v0, s[42:43] sc1
	s_mov_b64 s[44:45], -1
	s_waitcnt vmcnt(0)
	v_readfirstlane_b32 s29, v1
	s_cmp_gt_u32 s29, 31
	s_cbranch_scc1 .LBB0_1107
	s_sleep 1
	global_load_dword v1, v0, s[42:43] sc1
	s_waitcnt vmcnt(0)
	v_readfirstlane_b32 s29, v1
	s_cmp_lt_u32 s29, 32
	s_cbranch_scc0 .LBB0_1107
	s_sleep 1
	global_load_dword v1, v0, s[42:43] sc1
	s_waitcnt vmcnt(0)
	v_readfirstlane_b32 s29, v1
	s_cmp_lt_u32 s29, 32
	s_cbranch_scc0 .LBB0_1107
	s_sleep 1
	global_load_dword v1, v0, s[42:43] sc1
	s_waitcnt vmcnt(0)
	v_readfirstlane_b32 s29, v1
	s_cmp_lt_u32 s29, 32
	s_cbranch_scc0 .LBB0_1107
	s_sleep 1
	global_load_dword v1, v0, s[42:43] sc1
	s_waitcnt vmcnt(0)
	v_readfirstlane_b32 s29, v1
	s_cmp_lt_u32 s29, 32
	s_cbranch_scc0 .LBB0_1107
	s_add_i32 s28, s28, -5
	s_cmp_eq_u32 s28, 0
	s_cselect_b64 s[44:45], -1, 0
	s_sleep 1
	s_branch .LBB0_1107
.LBB0_1114:
	s_waitcnt vmcnt(0)
.LBB0_1115:
	s_or_b64 exec, exec, s[22:23]
	s_waitcnt vmcnt(0) lgkmcnt(0)
	s_barrier
	s_and_saveexec_b64 s[22:23], s[0:1]
	s_cbranch_execz .LBB0_1117
	s_lshl_b64 s[0:1], s[90:91], 13
	s_add_u32 s0, s33, s0
	s_addc_u32 s1, s46, s1
	s_waitcnt lgkmcnt(0)
	v_lshlrev_b64 v[0:1], 5, v[154:155]
	v_lshl_add_u64 v[0:1], s[0:1], 0, v[0:1]
	global_load_dword v2, v[0:1], off sc1
	global_load_dword v3, v[0:1], off offset:4 sc1
	global_load_dword v4, v[0:1], off offset:8 sc1
	global_load_dword v5, v[0:1], off offset:12 sc1
	global_load_dword v6, v[0:1], off offset:16 sc1
	global_load_dword v7, v[0:1], off offset:20 sc1
	global_load_dword v8, v[0:1], off offset:24 sc1
	s_nop 0
	global_load_dword v0, v[0:1], off offset:28 sc1
	v_mov_b32_e32 v1, 0x358637bd
	s_mov_b32 s0, 0x800000
	s_waitcnt vmcnt(7)
	v_add_f32_e32 v2, 0, v2
	s_waitcnt vmcnt(6)
	v_add_f32_e32 v2, v2, v3
	s_waitcnt vmcnt(5)
	v_add_f32_e32 v2, v2, v4
	s_waitcnt vmcnt(4)
	v_add_f32_e32 v2, v2, v5
	s_waitcnt vmcnt(3)
	v_add_f32_e32 v2, v2, v6
	s_waitcnt vmcnt(2)
	v_add_f32_e32 v2, v2, v7
	s_waitcnt vmcnt(1)
	v_add_f32_e32 v2, v2, v8
	s_waitcnt vmcnt(0)
	v_add_f32_e32 v0, v2, v0
	v_fmac_f32_e32 v1, 0x3a000000, v0
	v_mul_f32_e32 v0, 0x4b800000, v1
	v_cmp_gt_f32_e32 vcc, s0, v1
	s_nop 1
	v_cndmask_b32_e32 v0, v1, v0, vcc
	v_rsq_f32_e32 v0, v0
	s_nop 0
	v_mul_f32_e32 v1, 0x45800000, v0
	v_cndmask_b32_e32 v0, v0, v1, vcc
	v_lshl_add_u32 v1, v154, 2, 0
	ds_write_b32 v1, v0 offset:8192

; #define WG_BARRIER() do { asm volatile("s_waitcnt vmcnt(0) lgkmcnt(0)" ::: "memory"); __builtin_amdgcn_s_barrier(); asm volatile("" ::: "memory"); } while (0)
;     __device__ __forceinline__ void fused(AccT& acc, const Unit& u, int wr, int wc, int fr, int fq, LAS unsigned char* lds) const {
;     ...
;         if (wid == 0) { unsigned spins = 0;
;             while ((unsigned)__builtin_amdgcn_readfirstlane((int)__hip_atomic_load(cnt + 64 * u.pm, __ATOMIC_RELAXED, __HIP_MEMORY_SCOPE_AGENT)) < 32u) { __builtin_amdgcn_s_sleep(1); if (++spins > (1u << 22)) break; }
;             __builtin_amdgcn_fence(__ATOMIC_ACQUIRE, "agent");
;             asm volatile("s_waitcnt vmcnt(0)" ::: "memory"); }
;         WG_BARRIER();
;         if (tid < 256) { const unsigned* xp = X + ((size_t)u.pm * 256 + tid) * 8; float t = 0.f;
; #pragma unroll
;             for (int q = 0; q < 8; ++q) t += __uint_as_float(__hip_atomic_load(xp + q, __ATOMIC_RELAXED, __HIP_MEMORY_SCOPE_AGENT));
;             Ssh[tid] = rsqrtf(t * (1.0f / DM) + EPS); }
.LBB0_1147:
	s_waitcnt lgkmcnt(0)
	global_load_dword v1, v0, s[4:5] sc1
	s_waitcnt vmcnt(0)
	v_readfirstlane_b32 s6, v1
	s_cmp_gt_u32 s6, 31
	s_mov_b64 s[6:7], -1
	s_cbranch_scc1 .LBB0_1146
	s_sleep 1
	global_load_dword v1, v0, s[4:5] sc1
	s_waitcnt vmcnt(0)
	v_readfirstlane_b32 s6, v1
	s_cmp_lt_u32 s6, 32
	s_mov_b64 s[6:7], -1
	s_cbranch_scc0 .LBB0_1146
	s_sleep 1
	global_load_dword v1, v0, s[4:5] sc1
	s_waitcnt vmcnt(0)
	v_readfirstlane_b32 s6, v1
	s_cmp_lt_u32 s6, 32
	s_mov_b64 s[6:7], -1
	s_cbranch_scc0 .LBB0_1146
	s_sleep 1
	global_load_dword v1, v0, s[4:5] sc1
	s_waitcnt vmcnt(0)
	v_readfirstlane_b32 s6, v1
	s_cmp_lt_u32 s6, 32
	s_mov_b64 s[6:7], -1
	s_cbranch_scc0 .LBB0_1146
	s_sleep 1
	global_load_dword v1, v0, s[4:5] sc1
	s_waitcnt vmcnt(0)
	v_readfirstlane_b32 s6, v1
	s_cmp_lt_u32 s6, 32
	s_mov_b64 s[6:7], -1
	s_cbranch_scc0 .LBB0_1146
	s_add_i32 s22, s22, -5
	s_cmp_eq_u32 s22, 0
	s_cselect_b64 s[6:7], -1, 0
	s_sleep 1
	s_branch .LBB0_1146
.LBB0_1153:
	s_waitcnt vmcnt(0)
.LBB0_1154:
	s_or_b64 exec, exec, s[2:3]
	s_waitcnt vmcnt(0) lgkmcnt(0)
	s_barrier
	s_and_saveexec_b64 s[2:3], s[0:1]
	s_cbranch_execz .LBB0_1156
	s_lshl_b64 s[0:1], s[92:93], 13
	s_add_u32 s0, s33, s0
	s_addc_u32 s1, s46, s1
	s_waitcnt lgkmcnt(0)
	v_lshlrev_b64 v[0:1], 5, v[154:155]
	v_lshl_add_u64 v[0:1], s[0:1], 0, v[0:1]
	global_load_dword v2, v[0:1], off sc1
	global_load_dword v3, v[0:1], off offset:4 sc1
	global_load_dword v4, v[0:1], off offset:8 sc1
	global_load_dword v5, v[0:1], off offset:12 sc1
	global_load_dword v6, v[0:1], off offset:16 sc1
	global_load_dword v7, v[0:1], off offset:20 sc1
	global_load_dword v8, v[0:1], off offset:24 sc1
	s_nop 0
	global_load_dword v0, v[0:1], off offset:28 sc1
	v_mov_b32_e32 v1, 0x358637bd
	s_mov_b32 s0, 0x800000
	s_waitcnt vmcnt(7)
	v_add_f32_e32 v2, 0, v2
	s_waitcnt vmcnt(6)
	v_add_f32_e32 v2, v2, v3
	s_waitcnt vmcnt(5)
	v_add_f32_e32 v2, v2, v4
	s_waitcnt vmcnt(4)
	v_add_f32_e32 v2, v2, v5
	s_waitcnt vmcnt(3)
	v_add_f32_e32 v2, v2, v6
	s_waitcnt vmcnt(2)
	v_add_f32_e32 v2, v2, v7
	s_waitcnt vmcnt(1)
	v_add_f32_e32 v2, v2, v8
	s_waitcnt vmcnt(0)
	v_add_f32_e32 v0, v2, v0
	v_fmac_f32_e32 v1, 0x3a000000, v0
	v_mul_f32_e32 v0, 0x4b800000, v1
	v_cmp_gt_f32_e32 vcc, s0, v1
	s_nop 1
	v_cndmask_b32_e32 v0, v1, v0, vcc
	v_rsq_f32_e32 v0, v0
	s_nop 0
	v_mul_f32_e32 v1, 0x45800000, v0
	v_cndmask_b32_e32 v0, v0, v1, vcc
	v_lshl_add_u32 v1, v154, 2, 0
	ds_write_b32 v1, v0 offset:8192

; #define WG_BARRIER() do { asm volatile("s_waitcnt vmcnt(0) lgkmcnt(0)" ::: "memory"); __builtin_amdgcn_s_barrier(); asm volatile("" ::: "memory"); } while (0)
;     __device__ __forceinline__ void fused(AccT& acc, const Unit& u, int wr, int wc, int fr, int fq, LAS unsigned char* lds) const {
;     ...
;         if (wid == 0) { unsigned spins = 0;
;             while ((unsigned)__builtin_amdgcn_readfirstlane((int)__hip_atomic_load(cnt + 64 * u.pm, __ATOMIC_RELAXED, __HIP_MEMORY_SCOPE_AGENT)) < 32u) { __builtin_amdgcn_s_sleep(1); if (++spins > (1u << 22)) break; }
;             __builtin_amdgcn_fence(__ATOMIC_ACQUIRE, "agent");
;             asm volatile("s_waitcnt vmcnt(0)" ::: "memory"); }
;         WG_BARRIER();
;         if (tid < 256) { const unsigned* xp = X + ((size_t)u.pm * 256 + tid) * 8; float t = 0.f;
; #pragma unroll
;             for (int q = 0; q < 8; ++q) t += __uint_as_float(__hip_atomic_load(xp + q, __ATOMIC_RELAXED, __HIP_MEMORY_SCOPE_AGENT));
;             Ssh[tid] = rsqrtf(t * (1.0f / DM) + EPS); }
.LBB0_1310:
	s_waitcnt lgkmcnt(0)
	global_load_dword v1, v0, s[16:17] sc1
	s_waitcnt vmcnt(0)
	v_readfirstlane_b32 s18, v1
	s_cmp_gt_u32 s18, 31
	s_mov_b64 s[18:19], -1
	s_cbranch_scc1 .LBB0_1309
	s_sleep 1
	global_load_dword v1, v0, s[16:17] sc1
	s_waitcnt vmcnt(0)
	v_readfirstlane_b32 s18, v1
	s_cmp_lt_u32 s18, 32
	s_mov_b64 s[18:19], -1
	s_cbranch_scc0 .LBB0_1309
	s_sleep 1
	global_load_dword v1, v0, s[16:17] sc1
	s_waitcnt vmcnt(0)
	v_readfirstlane_b32 s18, v1
	s_cmp_lt_u32 s18, 32
	s_mov_b64 s[18:19], -1
	s_cbranch_scc0 .LBB0_1309
	s_sleep 1
	global_load_dword v1, v0, s[16:17] sc1
	s_waitcnt vmcnt(0)
	v_readfirstlane_b32 s18, v1
	s_cmp_lt_u32 s18, 32
	s_mov_b64 s[18:19], -1
	s_cbranch_scc0 .LBB0_1309
	s_sleep 1
	global_load_dword v1, v0, s[16:17] sc1
	s_waitcnt vmcnt(0)
	v_readfirstlane_b32 s18, v1
	s_cmp_lt_u32 s18, 32
	s_mov_b64 s[18:19], -1
	s_cbranch_scc0 .LBB0_1309
	s_add_i32 s31, s31, -5
	s_cmp_eq_u32 s31, 0
	s_cselect_b64 s[18:19], -1, 0
	s_sleep 1
	s_branch .LBB0_1309
.LBB0_1316:
	s_waitcnt vmcnt(0)
.LBB0_1317:
	s_or_b64 exec, exec, s[12:13]
	s_waitcnt vmcnt(0) lgkmcnt(0)
	s_barrier
	s_and_saveexec_b64 s[12:13], s[0:1]
	s_cbranch_execz .LBB0_1319
	s_lshl_b64 s[0:1], s[90:91], 13
	s_add_u32 s0, s22, s0
	s_addc_u32 s1, s23, s1
	s_waitcnt lgkmcnt(0)
	v_lshlrev_b64 v[0:1], 5, v[220:221]
	v_lshl_add_u64 v[0:1], s[0:1], 0, v[0:1]
	global_load_dword v2, v[0:1], off sc1
	global_load_dword v3, v[0:1], off offset:4 sc1
	global_load_dword v4, v[0:1], off offset:8 sc1
	global_load_dword v5, v[0:1], off offset:12 sc1
	global_load_dword v6, v[0:1], off offset:16 sc1
	global_load_dword v7, v[0:1], off offset:20 sc1
	global_load_dword v8, v[0:1], off offset:24 sc1
	s_nop 0
	global_load_dword v0, v[0:1], off offset:28 sc1
	v_mov_b32_e32 v1, 0x358637bd
	s_mov_b32 s0, 0x800000
	s_waitcnt vmcnt(7)
	v_add_f32_e32 v2, 0, v2
	s_waitcnt vmcnt(6)
	v_add_f32_e32 v2, v2, v3
	s_waitcnt vmcnt(5)
	v_add_f32_e32 v2, v2, v4
	s_waitcnt vmcnt(4)
	v_add_f32_e32 v2, v2, v5
	s_waitcnt vmcnt(3)
	v_add_f32_e32 v2, v2, v6
	s_waitcnt vmcnt(2)
	v_add_f32_e32 v2, v2, v7
	s_waitcnt vmcnt(1)
	v_add_f32_e32 v2, v2, v8
	s_waitcnt vmcnt(0)
	v_add_f32_e32 v0, v2, v0
	v_fmac_f32_e32 v1, 0x3a000000, v0
	v_mul_f32_e32 v0, 0x4b800000, v1
	v_cmp_gt_f32_e32 vcc, s0, v1
	s_nop 1
	v_cndmask_b32_e32 v0, v1, v0, vcc
	v_rsq_f32_e32 v0, v0
	s_nop 0
	v_mul_f32_e32 v1, 0x45800000, v0
	v_cndmask_b32_e32 v0, v0, v1, vcc
	v_lshl_add_u32 v1, v220, 2, 0
	ds_write_b32 v1, v0 offset:8192

; #define WG_BARRIER() do { asm volatile("s_waitcnt vmcnt(0) lgkmcnt(0)" ::: "memory"); __builtin_amdgcn_s_barrier(); asm volatile("" ::: "memory"); } while (0)
;     __device__ __forceinline__ void fused(AccT& acc, const Unit& u, int wr, int wc, int fr, int fq, LAS unsigned char* lds) const {
;     ...
;         if (wid == 0) { unsigned spins = 0;
;             while ((unsigned)__builtin_amdgcn_readfirstlane((int)__hip_atomic_load(cnt + 64 * u.pm, __ATOMIC_RELAXED, __HIP_MEMORY_SCOPE_AGENT)) < 32u) { __builtin_amdgcn_s_sleep(1); if (++spins > (1u << 22)) break; }
;             __builtin_amdgcn_fence(__ATOMIC_ACQUIRE, "agent");
;             asm volatile("s_waitcnt vmcnt(0)" ::: "memory"); }
;         WG_BARRIER();
;         if (tid < 256) { const unsigned* xp = X + ((size_t)u.pm * 256 + tid) * 8; float t = 0.f;
; #pragma unroll
;             for (int q = 0; q < 8; ++q) t += __uint_as_float(__hip_atomic_load(xp + q, __ATOMIC_RELAXED, __HIP_MEMORY_SCOPE_AGENT));
;             Ssh[tid] = rsqrtf(t * (1.0f / DM) + EPS); }
.LBB0_1349:
	s_waitcnt lgkmcnt(0)
	global_load_dword v1, v0, s[4:5] sc1
	s_waitcnt vmcnt(0)
	v_readfirstlane_b32 s6, v1
	s_cmp_gt_u32 s6, 31
	s_mov_b64 s[6:7], -1
	s_cbranch_scc1 .LBB0_1348
	s_sleep 1
	global_load_dword v1, v0, s[4:5] sc1
	s_waitcnt vmcnt(0)
	v_readfirstlane_b32 s6, v1
	s_cmp_lt_u32 s6, 32
	s_mov_b64 s[6:7], -1
	s_cbranch_scc0 .LBB0_1348
	s_sleep 1
	global_load_dword v1, v0, s[4:5] sc1
	s_waitcnt vmcnt(0)
	v_readfirstlane_b32 s6, v1
	s_cmp_lt_u32 s6, 32
	s_mov_b64 s[6:7], -1
	s_cbranch_scc0 .LBB0_1348
	s_sleep 1
	global_load_dword v1, v0, s[4:5] sc1
	s_waitcnt vmcnt(0)
	v_readfirstlane_b32 s6, v1
	s_cmp_lt_u32 s6, 32
	s_mov_b64 s[6:7], -1
	s_cbranch_scc0 .LBB0_1348
	s_sleep 1
	global_load_dword v1, v0, s[4:5] sc1
	s_waitcnt vmcnt(0)
	v_readfirstlane_b32 s6, v1
	s_cmp_lt_u32 s6, 32
	s_mov_b64 s[6:7], -1
	s_cbranch_scc0 .LBB0_1348
	s_add_i32 s8, s8, -5
	s_cmp_eq_u32 s8, 0
	s_cselect_b64 s[6:7], -1, 0
	s_sleep 1
	s_branch .LBB0_1348
.LBB0_1355:
	s_waitcnt vmcnt(0)
.LBB0_1356:
	s_or_b64 exec, exec, s[2:3]
	s_waitcnt vmcnt(0) lgkmcnt(0)
	s_barrier
	s_and_saveexec_b64 s[2:3], s[0:1]
	s_cbranch_execz .LBB0_1358
	s_lshl_b64 s[0:1], s[92:93], 13
	s_add_u32 s0, s22, s0
	s_addc_u32 s1, s23, s1
	s_waitcnt lgkmcnt(0)
	v_lshlrev_b64 v[0:1], 5, v[200:201]
	v_lshl_add_u64 v[0:1], s[0:1], 0, v[0:1]
	global_load_dword v2, v[0:1], off sc1
	global_load_dword v3, v[0:1], off offset:4 sc1
	global_load_dword v4, v[0:1], off offset:8 sc1
	global_load_dword v5, v[0:1], off offset:12 sc1
	global_load_dword v6, v[0:1], off offset:16 sc1
	global_load_dword v7, v[0:1], off offset:20 sc1
	global_load_dword v8, v[0:1], off offset:24 sc1
	s_nop 0
	global_load_dword v0, v[0:1], off offset:28 sc1
	v_mov_b32_e32 v1, 0x358637bd
	s_mov_b32 s0, 0x800000
	s_waitcnt vmcnt(7)
	v_add_f32_e32 v2, 0, v2
	s_waitcnt vmcnt(6)
	v_add_f32_e32 v2, v2, v3
	s_waitcnt vmcnt(5)
	v_add_f32_e32 v2, v2, v4
	s_waitcnt vmcnt(4)
	v_add_f32_e32 v2, v2, v5
	s_waitcnt vmcnt(3)
	v_add_f32_e32 v2, v2, v6
	s_waitcnt vmcnt(2)
	v_add_f32_e32 v2, v2, v7
	s_waitcnt vmcnt(1)
	v_add_f32_e32 v2, v2, v8
	s_waitcnt vmcnt(0)
	v_add_f32_e32 v0, v2, v0
	v_fmac_f32_e32 v1, 0x3a000000, v0
	v_mul_f32_e32 v0, 0x4b800000, v1
	v_cmp_gt_f32_e32 vcc, s0, v1
	s_nop 1
	v_cndmask_b32_e32 v0, v1, v0, vcc
	v_rsq_f32_e32 v0, v0
	s_nop 0
	v_mul_f32_e32 v1, 0x45800000, v0
	v_cndmask_b32_e32 v0, v0, v1, vcc
	v_lshl_add_u32 v1, v200, 2, 0
	ds_write_b32 v1, v0 offset:8192
